# hyena order-0: next chunk's short-conv/pack VALU moved under the second half of the current chunk's Toeplitz MFMA steps
# baseline (speedup 1.0000x reference)
.LBB0_665:
.Lhy0_next:
	s_mov_b32 s8, 0
	v_add_u32_e32 v14, s8, v83
	v_add_u32_e32 v0, s8, v84
	ds_read_b128 v[2:5], v14 offset:64
	ds_read_b128 v[6:9], v0
	ds_read_b128 v[10:13], v14
	s_waitcnt lgkmcnt(1)
	v_mfma_f32_32x32x16_bf16 v[32:47], v[2:5], v[6:9], v[32:47]
	s_waitcnt lgkmcnt(0)
	v_mfma_f32_32x32x16_bf16 v[16:31], v[10:13], v[6:9], v[16:31]
	ds_read_b128 v[6:9], v14 offset:96
	ds_read_b128 v[10:13], v0 offset:32
	ds_read_b128 v[88:91], v14 offset:32
	s_waitcnt lgkmcnt(1)
	v_mfma_f32_32x32x16_bf16 v[32:47], v[6:9], v[10:13], v[32:47]
	s_waitcnt lgkmcnt(0)
	v_mfma_f32_32x32x16_bf16 v[16:31], v[88:91], v[10:13], v[16:31]
	ds_read_b128 v[10:13], v14 offset:128
	ds_read_b128 v[88:91], v0 offset:64
	s_waitcnt lgkmcnt(0)
	v_mfma_f32_32x32x16_bf16 v[32:47], v[10:13], v[88:91], v[32:47]
	v_mfma_f32_32x32x16_bf16 v[16:31], v[2:5], v[88:91], v[16:31]
	ds_read_b128 v[2:5], v14 offset:160
	ds_read_b128 v[88:91], v0 offset:96
	s_waitcnt lgkmcnt(0)
	v_mfma_f32_32x32x16_bf16 v[32:47], v[2:5], v[88:91], v[32:47]
	v_mfma_f32_32x32x16_bf16 v[16:31], v[6:9], v[88:91], v[16:31]
	ds_read_b128 v[6:9], v14 offset:192
	ds_read_b128 v[88:91], v0 offset:128
	s_waitcnt lgkmcnt(0)
	v_mfma_f32_32x32x16_bf16 v[32:47], v[6:9], v[88:91], v[32:47]
	v_mfma_f32_32x32x16_bf16 v[16:31], v[10:13], v[88:91], v[16:31]
	ds_read_b128 v[10:13], v14 offset:224
	ds_read_b128 v[88:91], v0 offset:160
	s_waitcnt lgkmcnt(0)
	v_mfma_f32_32x32x16_bf16 v[32:47], v[10:13], v[88:91], v[32:47]
	v_mfma_f32_32x32x16_bf16 v[16:31], v[2:5], v[88:91], v[16:31]
	ds_read_b128 v[2:5], v14 offset:256
	ds_read_b128 v[88:91], v0 offset:192
	s_waitcnt lgkmcnt(0)
	v_mfma_f32_32x32x16_bf16 v[32:47], v[2:5], v[88:91], v[32:47]
	v_mfma_f32_32x32x16_bf16 v[16:31], v[6:9], v[88:91], v[16:31]
	ds_read_b128 v[2:5], v14 offset:288
	ds_read_b128 v[6:9], v0 offset:224
	s_waitcnt lgkmcnt(0)
	v_mfma_f32_32x32x16_bf16 v[32:47], v[2:5], v[6:9], v[32:47]
	v_mfma_f32_32x32x16_bf16 v[16:31], v[10:13], v[6:9], v[16:31]
	s_cmp_eq_u32 s10, 8
	s_cbranch_scc1 .Lhy0_last
	s_waitcnt vmcnt(0)
	s_movk_i32 s8, 0x100
	v_add_u32_e32 v14, s8, v83
	v_add_u32_e32 v0, s8, v84
	ds_read_b128 v[2:5], v14 offset:64
	ds_read_b128 v[6:9], v0
	ds_read_b128 v[10:13], v14
	s_waitcnt lgkmcnt(1)
	v_mfma_f32_32x32x16_bf16 v[32:47], v[2:5], v[6:9], v[32:47]
	s_waitcnt lgkmcnt(0)
	v_mfma_f32_32x32x16_bf16 v[16:31], v[10:13], v[6:9], v[16:31]
	v_and_b32_e32 v238, 0xffff0000, v48
	v_lshlrev_b32_e32 v246, 16, v49
	v_lshlrev_b32_e32 v237, 16, v48
	v_mov_b32_e32 v236, v238
	v_mov_b32_e32 v244, v246
	v_mov_b32_e32 v245, v238
	v_lshlrev_b32_e32 v240, 16, v76
	v_pk_mul_f32 v[242:243], v[64:65], v[236:237]
	v_pk_mul_f32 v[244:245], v[64:65], v[244:245]
	v_and_b32_e32 v239, 0xffff0000, v49
	v_fma_f32 v240, v62, v240, v243
	v_fma_f32 v236, v62, v237, v245
	v_add_f32_e32 v240, v242, v240
	v_pk_mul_f32 v[242:243], v[62:63], v[238:239]
	ds_read_b128 v[6:9], v14 offset:96
	ds_read_b128 v[10:13], v0 offset:32
	ds_read_b128 v[88:91], v14 offset:32
	s_waitcnt lgkmcnt(1)
	v_mfma_f32_32x32x16_bf16 v[32:47], v[6:9], v[10:13], v[32:47]
	s_waitcnt lgkmcnt(0)
	v_mfma_f32_32x32x16_bf16 v[16:31], v[88:91], v[10:13], v[16:31]
	v_add_f32_e32 v236, v244, v236
	v_add_f32_e32 v248, v73, v236
	v_fma_f32 v236, v65, v246, v242
	v_lshlrev_b32_e32 v247, 16, v50
	v_add_f32_e32 v236, v243, v236
	v_add_f32_e32 v249, v73, v236
	v_pk_mul_f32 v[236:237], v[62:63], v[246:247]
	v_lshlrev_b32_e32 v242, 16, v51
	v_fma_f32 v236, v65, v239, v236
	v_add_f32_e32 v236, v237, v236
	v_add_f32_e32 v246, v73, v236
	v_and_b32_e32 v236, 0xffff0000, v50
	v_mov_b32_e32 v238, v236
	v_pk_mul_f32 v[238:239], v[66:67], v[238:239]
	ds_read_b128 v[10:13], v14 offset:128
	ds_read_b128 v[88:91], v0 offset:64
	s_waitcnt lgkmcnt(0)
	v_mfma_f32_32x32x16_bf16 v[32:47], v[10:13], v[88:91], v[32:47]
	v_mfma_f32_32x32x16_bf16 v[16:31], v[2:5], v[88:91], v[16:31]
	v_mov_b32_e32 v244, v242
	v_fma_f32 v239, v65, v247, v239
	v_mov_b32_e32 v245, v236
	v_and_b32_e32 v237, 0xffff0000, v51
	v_add_f32_e32 v238, v238, v239
	v_pk_mul_f32 v[244:245], v[64:65], v[244:245]
	v_add_f32_e32 v250, v73, v238
	v_pk_mul_f32 v[238:239], v[62:63], v[236:237]
	v_fma_f32 v236, v62, v247, v245
	v_add_f32_e32 v236, v244, v236
	v_lshlrev_b32_e32 v243, 16, v78
	v_add_f32_e32 v247, v73, v236
	v_fma_f32 v236, v65, v242, v238
	v_add_f32_e32 v236, v239, v236
	ds_read_b128 v[2:5], v14 offset:160
	ds_read_b128 v[88:91], v0 offset:96
	s_waitcnt lgkmcnt(0)
	v_mfma_f32_32x32x16_bf16 v[32:47], v[2:5], v[88:91], v[32:47]
	v_mfma_f32_32x32x16_bf16 v[16:31], v[6:9], v[88:91], v[16:31]
	v_pk_mul_f32 v[238:239], v[62:63], v[242:243]
	v_add_f32_e32 v244, v73, v236
	v_fma_f32 v236, v65, v237, v238
	v_add_f32_e32 v236, v236, v239
	v_add_f32_e32 v240, v73, v240
	v_add_f32_e32 v239, v73, v236
	v_cvt_pk_bf16_f32 v236, v240, v248
	v_cvt_pk_bf16_f32 v237, v249, v246
	v_cvt_pk_bf16_f32 v238, v250, v247
	v_cvt_pk_bf16_f32 v239, v244, v239
	v_mov_b32_e32 v48, v236
	v_mov_b32_e32 v49, v237
	v_mov_b32_e32 v50, v238
	v_mov_b32_e32 v51, v239
	ds_read_b128 v[6:9], v14 offset:192
	ds_read_b128 v[88:91], v0 offset:128
	s_waitcnt lgkmcnt(0)
	v_mfma_f32_32x32x16_bf16 v[32:47], v[6:9], v[88:91], v[32:47]
	v_mfma_f32_32x32x16_bf16 v[16:31], v[10:13], v[88:91], v[16:31]
	v_and_b32_e32 v238, 0xffff0000, v52
	v_lshlrev_b32_e32 v246, 16, v53
	v_lshlrev_b32_e32 v237, 16, v52
	v_mov_b32_e32 v236, v238
	v_mov_b32_e32 v244, v246
	v_mov_b32_e32 v245, v238
	v_lshlrev_b32_e32 v240, 16, v77
	v_pk_mul_f32 v[242:243], v[64:65], v[236:237]
	v_pk_mul_f32 v[244:245], v[64:65], v[244:245]
	v_and_b32_e32 v239, 0xffff0000, v53
	v_fma_f32 v240, v62, v240, v243
	v_fma_f32 v236, v62, v237, v245
	v_add_f32_e32 v240, v242, v240
	v_pk_mul_f32 v[242:243], v[62:63], v[238:239]
	ds_read_b128 v[10:13], v14 offset:224
	ds_read_b128 v[88:91], v0 offset:160
	s_waitcnt lgkmcnt(0)
	v_mfma_f32_32x32x16_bf16 v[32:47], v[10:13], v[88:91], v[32:47]
	v_mfma_f32_32x32x16_bf16 v[16:31], v[2:5], v[88:91], v[16:31]
	v_add_f32_e32 v236, v244, v236
	v_add_f32_e32 v248, v73, v236
	v_fma_f32 v236, v65, v246, v242
	v_lshlrev_b32_e32 v247, 16, v54
	v_add_f32_e32 v236, v243, v236
	v_add_f32_e32 v249, v73, v236
	v_pk_mul_f32 v[236:237], v[62:63], v[246:247]
	v_lshlrev_b32_e32 v242, 16, v55
	v_fma_f32 v236, v65, v239, v236
	v_add_f32_e32 v236, v237, v236
	v_add_f32_e32 v246, v73, v236
	v_and_b32_e32 v236, 0xffff0000, v54
	v_mov_b32_e32 v238, v236
	v_pk_mul_f32 v[238:239], v[66:67], v[238:239]
	ds_read_b128 v[2:5], v14 offset:256
	ds_read_b128 v[88:91], v0 offset:192
	s_waitcnt lgkmcnt(0)
	v_mfma_f32_32x32x16_bf16 v[32:47], v[2:5], v[88:91], v[32:47]
	v_mfma_f32_32x32x16_bf16 v[16:31], v[6:9], v[88:91], v[16:31]
	v_mov_b32_e32 v244, v242
	v_fma_f32 v239, v65, v247, v239
	v_mov_b32_e32 v245, v236
	v_and_b32_e32 v237, 0xffff0000, v55
	v_add_f32_e32 v238, v238, v239
	v_pk_mul_f32 v[244:245], v[64:65], v[244:245]
	v_add_f32_e32 v250, v73, v238
	v_pk_mul_f32 v[238:239], v[62:63], v[236:237]
	v_fma_f32 v236, v62, v247, v245
	v_add_f32_e32 v236, v244, v236
	v_lshlrev_b32_e32 v243, 16, v82
	v_add_f32_e32 v247, v73, v236
	v_fma_f32 v236, v65, v242, v238
	v_add_f32_e32 v236, v239, v236
	ds_read_b128 v[2:5], v14 offset:288
	ds_read_b128 v[6:9], v0 offset:224
	s_waitcnt lgkmcnt(0)
	v_mfma_f32_32x32x16_bf16 v[32:47], v[2:5], v[6:9], v[32:47]
	v_mfma_f32_32x32x16_bf16 v[16:31], v[10:13], v[6:9], v[16:31]
	v_pk_mul_f32 v[238:239], v[62:63], v[242:243]
	v_add_f32_e32 v244, v73, v236
	v_fma_f32 v236, v65, v237, v238
	v_add_f32_e32 v236, v236, v239
	v_add_f32_e32 v239, v73, v236
	v_add_f32_e32 v240, v73, v240
	v_cvt_pk_bf16_f32 v236, v240, v248
	v_cvt_pk_bf16_f32 v237, v249, v246
	v_cvt_pk_bf16_f32 v238, v250, v247
	v_cvt_pk_bf16_f32 v239, v244, v239
	s_waitcnt lgkmcnt(0)
	s_barrier
	ds_write_b128 v85, v[48:51] offset:41216
	ds_write_b128 v86, v[236:239] offset:41216
	s_waitcnt lgkmcnt(0)
	s_barrier
	s_mov_b32 s8, s10
	s_add_i32 s10, s10, 1
	s_cmp_eq_u32 s8, 7
	s_cbranch_scc1 .Lhy0_nopref
	v_lshl_or_b32 v6, s10, 8, v75
	v_lshlrev_b32_e32 v0, 1, v6
	v_lshl_add_u64 v[2:3], s[0:1], 0, v[0:1]
	v_lshl_add_u64 v[4:5], v[2:3], 0, v[68:69]
	global_load_dwordx4 v[48:51], v[4:5], off offset:512
	global_load_ushort v76, v[4:5], off offset:510
	s_movk_i32 s8, 0x7f8
	v_cmp_ne_u32_e32 vcc, s8, v6
	v_mov_b32_e32 v82, 0
	v_mov_b32_e32 v78, 0
	s_and_saveexec_b64 s[8:9], vcc
	s_cbranch_execz .Lhy0_p662b
	global_load_ushort v78, v[4:5], off offset:528

.Lhy0_nopref:
	v_add_u32_e32 v83, 0x200, v83
	s_branch .Lhy0_next
.Lhy0_last:
	s_movk_i32 s8, 0x100
	v_add_u32_e32 v14, s8, v83
	v_add_u32_e32 v0, s8, v84
	ds_read_b128 v[2:5], v14 offset:64
	ds_read_b128 v[6:9], v0
	ds_read_b128 v[10:13], v14
	s_waitcnt lgkmcnt(1)
	v_mfma_f32_32x32x16_bf16 v[32:47], v[2:5], v[6:9], v[32:47]
	s_waitcnt lgkmcnt(0)
	v_mfma_f32_32x32x16_bf16 v[16:31], v[10:13], v[6:9], v[16:31]
	ds_read_b128 v[6:9], v14 offset:96
	ds_read_b128 v[10:13], v0 offset:32
	ds_read_b128 v[88:91], v14 offset:32
	s_waitcnt lgkmcnt(1)
	v_mfma_f32_32x32x16_bf16 v[32:47], v[6:9], v[10:13], v[32:47]
	s_waitcnt lgkmcnt(0)
	v_mfma_f32_32x32x16_bf16 v[16:31], v[88:91], v[10:13], v[16:31]
	ds_read_b128 v[10:13], v14 offset:128
	ds_read_b128 v[88:91], v0 offset:64
	s_waitcnt lgkmcnt(0)
	v_mfma_f32_32x32x16_bf16 v[32:47], v[10:13], v[88:91], v[32:47]
	v_mfma_f32_32x32x16_bf16 v[16:31], v[2:5], v[88:91], v[16:31]
	ds_read_b128 v[2:5], v14 offset:160
	ds_read_b128 v[88:91], v0 offset:96
	s_waitcnt lgkmcnt(0)
	v_mfma_f32_32x32x16_bf16 v[32:47], v[2:5], v[88:91], v[32:47]
	v_mfma_f32_32x32x16_bf16 v[16:31], v[6:9], v[88:91], v[16:31]
	ds_read_b128 v[6:9], v14 offset:192
	ds_read_b128 v[88:91], v0 offset:128
	s_waitcnt lgkmcnt(0)
	v_mfma_f32_32x32x16_bf16 v[32:47], v[6:9], v[88:91], v[32:47]
	v_mfma_f32_32x32x16_bf16 v[16:31], v[10:13], v[88:91], v[16:31]
	ds_read_b128 v[10:13], v14 offset:224
	ds_read_b128 v[88:91], v0 offset:160
	s_waitcnt lgkmcnt(0)
	v_mfma_f32_32x32x16_bf16 v[32:47], v[10:13], v[88:91], v[32:47]
	v_mfma_f32_32x32x16_bf16 v[16:31], v[2:5], v[88:91], v[16:31]
	ds_read_b128 v[2:5], v14 offset:256
	ds_read_b128 v[88:91], v0 offset:192
	s_waitcnt lgkmcnt(0)
	v_mfma_f32_32x32x16_bf16 v[32:47], v[2:5], v[88:91], v[32:47]
	v_mfma_f32_32x32x16_bf16 v[16:31], v[6:9], v[88:91], v[16:31]
	ds_read_b128 v[2:5], v14 offset:288
	ds_read_b128 v[6:9], v0 offset:224
	s_waitcnt lgkmcnt(0)
	v_mfma_f32_32x32x16_bf16 v[32:47], v[2:5], v[6:9], v[32:47]
	v_mfma_f32_32x32x16_bf16 v[16:31], v[10:13], v[6:9], v[16:31]
	v_add_u32_e32 v83, 0x200, v83
	v_lshrrev_b32_e32 v0, 6, v61
	s_movk_i32 s0, 0x1080
	v_mul_lo_u32 v0, v0, s0
	s_add_i32 s0, 0, 0x10000
	s_waitcnt vmcnt(3)
	v_and_b32_e32 v50, 16, v81
	s_waitcnt vmcnt(1)
	v_add_u32_e32 v53, s0, v0
	v_lshrrev_b32_e32 v54, 1, v80
	v_or_b32_e32 v51, s12, v50
	v_lshl_add_u32 v52, v79, 2, v53
	v_mul_u32_u24_e32 v0, 0x900, v54
	v_or_b32_e32 v2, s6, v51
	v_mov_b32_e32 v3, s7
	v_lshl_add_u64 v[2:3], v[0:1], 0, v[2:3]
	s_mov_b64 s[0:1], 0x100
	v_mad_u32_u24 v0, v74, s60, v52
	v_and_b32_e32 v14, 0xffffffc0, v61
	v_lshl_add_u64 v[48:49], v[2:3], 0, s[0:1]
	v_add_u32_e32 v2, 0x400, v0
	ds_write2_b32 v0, v32, v33 offset1:33
	ds_write2_b32 v0, v34, v35 offset0:66 offset1:99
	ds_write2_b32 v2, v36, v37 offset0:8 offset1:41
	ds_write2_b32 v2, v38, v39 offset0:74 offset1:107
	v_add_u32_e32 v2, 0x800, v0
	v_add_u32_e32 v0, 0xc00, v0
	v_ashrrev_i32_e32 v15, 31, v14
	v_readlane_b32 s0, v254, 0
	ds_write2_b32 v2, v40, v41 offset0:16 offset1:49
	ds_write2_b32 v2, v42, v43 offset0:82 offset1:115
	ds_write2_b32 v0, v44, v45 offset0:24 offset1:57
	ds_write2_b32 v0, v46, v47 offset0:90 offset1:123
	v_lshl_add_u64 v[36:37], v[48:49], 0, v[14:15]
	v_readlane_b32 s1, v254, 1
	s_waitcnt lgkmcnt(0)
	v_add_u32_e32 v4, v51, v14
	v_cmp_lt_i32_e32 vcc, 0, v4
	v_lshl_add_u64 v[2:3], v[36:37], 1, s[0:1]
	global_load_dwordx4 v[10:13], v[2:3], off offset:16
	global_load_dwordx4 v[32:35], v[2:3], off
	v_mov_b32_e32 v0, 0
	v_mov_b32_e32 v38, 0
	s_and_saveexec_b64 s[0:1], vcc
	s_cbranch_execz .LBB0_670
	global_load_ushort v5, v[2:3], off offset:-2
	s_waitcnt vmcnt(0)
	v_lshlrev_b32_e32 v38, 16, v5
